# ev_out: residual-input and gain loads issued before the K-loop (registers unused by the 128x64 K-loop); epilogue only waits, fmacs and stores
# speedup vs baseline: 1.0046x; 1.0046x over previous
.Leo_item:
	s_mul_hi_i32 s12, s9, 0x2aaaaaab
	s_lshr_b32 s13, s12, 31
	s_ashr_i32 s12, s12, 4
	s_add_i32 s12, s12, s13
	s_mul_i32 s13, s12, 0x60
	s_sub_i32 s13, s9, s13
	s_lshl_b32 s10, s13, 7
	s_lshl_b32 s11, s12, 6
	v_lshl_or_b32 v80, v183, 3, v191
	v_and_b32_e32 v81, 31, v80
	v_bfe_u32 v82, v80, 6, 1
	v_mul_u32_u24_e32 v82, 32, v82
	v_add_u32_e32 v82, v82, v81
	v_lshlrev_b32_e32 v84, 2, v82
	v_bfe_u32 v82, v80, 7, 1
	v_lshlrev_b32_e32 v82, 4, v82
	v_bfe_u32 v87, v80, 5, 1
	v_or_b32_e32 v82, v82, v87
	v_lshl_add_u32 v83, v82, 14, v84
	s_sub_u32 s100, s10, 0x2000
	s_lshr_b32 s100, s100, 11
	s_add_u32 s100, s100, 1
	s_cmp_lt_u32 s10, 0x2000
	s_cmov_b32 s100, 0
	s_mul_i32 s100, s100, 0x6000
	s_lshl_b32 s101, s11, 2
	s_add_u32 s100, s100, s101
	s_add_u32 s100, s100, 0x3442000
	v_add_u32_e32 v84, s100, v84
	global_load_dword v85, v84, s[90:91]
	s_lshl_b32 s100, s10, 12
	s_add_u32 s100, s100, s101
	s_add_u32 s98, s88, s100
	s_addc_u32 s99, s89, 0
	s_lshl_b32 s100, s10, 12
	s_add_u32 s100, s100, s101
	s_sub_u32 s15, s100, 0x2000000
	s_cmp_lt_u32 s10, 0x2000
	s_cselect_b32 s15, s100, s15
	s_cselect_b32 s100, s72, s74
	s_cselect_b32 s101, s73, s75
	s_add_u32 s100, s100, s15
	s_addc_u32 s101, s101, 0
	s_mov_b32 s16, s100
	s_mov_b32 s17, s101
	global_load_dword v96, v83, s[16:17] offset:0
	s_add_u32 s16, s16, 0x1000
	s_addc_u32 s17, s17, 0
	global_load_dword v97, v83, s[16:17] offset:0
	s_add_u32 s16, s16, 0x1000
	s_addc_u32 s17, s17, 0
	global_load_dword v98, v83, s[16:17] offset:0
	s_add_u32 s16, s16, 0x1000
	s_addc_u32 s17, s17, 0
	global_load_dword v99, v83, s[16:17] offset:0
	s_add_u32 s16, s16, 0x5000
	s_addc_u32 s17, s17, 0
	global_load_dword v100, v83, s[16:17] offset:0
	s_add_u32 s16, s16, 0x1000
	s_addc_u32 s17, s17, 0
	global_load_dword v101, v83, s[16:17] offset:0
	s_add_u32 s16, s16, 0x1000
	s_addc_u32 s17, s17, 0
	global_load_dword v102, v83, s[16:17] offset:0
	s_add_u32 s16, s16, 0x1000
	s_addc_u32 s17, s17, 0
	global_load_dword v103, v83, s[16:17] offset:0
	s_add_u32 s16, s16, 0x5000
	s_addc_u32 s17, s17, 0
	global_load_dword v104, v83, s[16:17] offset:0
	s_add_u32 s16, s16, 0x1000
	s_addc_u32 s17, s17, 0
	global_load_dword v105, v83, s[16:17] offset:0
	s_add_u32 s16, s16, 0x1000
	s_addc_u32 s17, s17, 0
	global_load_dword v106, v83, s[16:17] offset:0
	s_add_u32 s16, s16, 0x1000
	s_addc_u32 s17, s17, 0
	global_load_dword v107, v83, s[16:17] offset:0
	s_add_u32 s16, s16, 0x5000
	s_addc_u32 s17, s17, 0
	global_load_dword v108, v83, s[16:17] offset:0
	s_add_u32 s16, s16, 0x1000
	s_addc_u32 s17, s17, 0
	global_load_dword v109, v83, s[16:17] offset:0
	s_add_u32 s16, s16, 0x1000
	s_addc_u32 s17, s17, 0
	global_load_dword v110, v83, s[16:17] offset:0
	s_add_u32 s16, s16, 0x1000
	s_addc_u32 s17, s17, 0
	global_load_dword v111, v83, s[16:17] offset:0
	s_add_u32 s16, s16, 0x5000
	s_addc_u32 s17, s17, 0
	global_load_dword v112, v83, s[16:17] offset:0
	s_add_u32 s16, s16, 0x1000
	s_addc_u32 s17, s17, 0
	global_load_dword v113, v83, s[16:17] offset:0
	s_add_u32 s16, s16, 0x1000
	s_addc_u32 s17, s17, 0
	global_load_dword v114, v83, s[16:17] offset:0
	s_add_u32 s16, s16, 0x1000
	s_addc_u32 s17, s17, 0
	global_load_dword v115, v83, s[16:17] offset:0
	s_add_u32 s16, s16, 0x5000
	s_addc_u32 s17, s17, 0
	global_load_dword v116, v83, s[16:17] offset:0
	s_add_u32 s16, s16, 0x1000
	s_addc_u32 s17, s17, 0
	global_load_dword v117, v83, s[16:17] offset:0
	s_add_u32 s16, s16, 0x1000
	s_addc_u32 s17, s17, 0
	global_load_dword v118, v83, s[16:17] offset:0
	s_add_u32 s16, s16, 0x1000
	s_addc_u32 s17, s17, 0
	global_load_dword v119, v83, s[16:17] offset:0
	s_add_u32 s16, s16, 0x5000
	s_addc_u32 s17, s17, 0
	global_load_dword v120, v83, s[16:17] offset:0
	s_add_u32 s16, s16, 0x1000
	s_addc_u32 s17, s17, 0
	global_load_dword v121, v83, s[16:17] offset:0
	s_add_u32 s16, s16, 0x1000
	s_addc_u32 s17, s17, 0
	global_load_dword v122, v83, s[16:17] offset:0
	s_add_u32 s16, s16, 0x1000
	s_addc_u32 s17, s17, 0
	global_load_dword v123, v83, s[16:17] offset:0
	s_add_u32 s16, s16, 0x5000
	s_addc_u32 s17, s17, 0
	global_load_dword v124, v83, s[16:17] offset:0
	s_add_u32 s16, s16, 0x1000
	s_addc_u32 s17, s17, 0
	global_load_dword v125, v83, s[16:17] offset:0
	s_add_u32 s16, s16, 0x1000
	s_addc_u32 s17, s17, 0
	global_load_dword v126, v83, s[16:17] offset:0
	s_add_u32 s16, s16, 0x1000
	s_addc_u32 s17, s17, 0
	global_load_dword v127, v83, s[16:17] offset:0
	v_lshl_or_b32 v32, v183, 3, v191
	v_and_b32_e32 v33, 63, v32
	v_lshrrev_b32_e32 v34, 3, v33
	v_lshrrev_b32_e32 v35, 4, v33
	v_xor_b32_e32 v35, v35, v33
	v_and_b32_e32 v35, 7, v35
	v_lshlrev_b32_e32 v35, 4, v35
	s_movk_i32 s12, 0x800
	v_mad_u32_u24 v68, v34, s12, v35
	v_xor_b32_e32 v36, 64, v68
	v_add_u32_e32 v69, 0x3c00, v36
	v_add_u32_e32 v70, 0x7800, v68
	v_add_u32_e32 v71, 0xb400, v36
	v_and_b32_e32 v37, 31, v32
	v_bfe_u32 v38, v32, 5, 1
	v_bfe_u32 v39, v32, 1, 3
	v_xor_b32_e32 v39, v39, v38
	v_lshlrev_b32_e32 v39, 4, v39
	v_bfe_u32 v40, v32, 7, 1
	v_lshl_or_b32 v40, v40, 6, v37
	v_lshl_add_u32 v72, v40, 7, v39
	v_bfe_u32 v41, v32, 6, 1
	v_lshl_or_b32 v41, v41, 5, v37
	v_lshl_add_u32 v76, v41, 7, v39
	v_add_u32_e32 v76, 0x4000, v76
	v_xor_b32_e32 v73, 32, v72
	v_xor_b32_e32 v77, 32, v76
	v_xor_b32_e32 v74, 64, v72
	v_xor_b32_e32 v78, 64, v76
	v_xor_b32_e32 v75, 96, v72
	v_xor_b32_e32 v79, 96, v76
	v_lshrrev_b32_e32 v42, 6, v32
	s_nop 0
	v_readfirstlane_b32 s13, v42
	s_nop 3
	s_lshl_b32 s6, s13, 12
	s_lshl_b32 s7, s13, 11
	s_add_u32 s7, s7, 0x4000
	s_lshl_b32 s12, s13, 5
	s_add_u32 s12, s12, s10
	s_mul_i32 s12, s12, 0x800
	s_add_u32 s12, s12, 0x3000000
	s_add_u32 s0, s88, s12
	s_addc_u32 s1, s89, 0
	s_lshl_b32 s12, s13, 4
	s_add_u32 s12, s12, s11
	s_mul_i32 s12, s12, 0x800
	s_add_u32 s12, s12, 0x940000
	s_add_u32 s2, s90, s12
	s_addc_u32 s3, s91, 0
	s_add_u32 m0, s6, 0x0
	s_nop 0
	global_load_lds_dwordx4 v68, s[0:1] offset:0
	global_load_lds_dwordx4 v69, s[0:1] offset:1024
	global_load_lds_dwordx4 v70, s[0:1] offset:2048
	global_load_lds_dwordx4 v71, s[0:1] offset:3072
	s_add_u32 m0, s7, 0x0
	s_nop 0
	global_load_lds_dwordx4 v68, s[2:3] offset:0
	global_load_lds_dwordx4 v69, s[2:3] offset:1024
	s_add_u32 s0, s0, 0x80
	s_addc_u32 s1, s1, 0
	s_add_u32 s2, s2, 0x80
	s_addc_u32 s3, s3, 0
	s_add_u32 m0, s6, 0x8000
	s_nop 0
	global_load_lds_dwordx4 v68, s[0:1] offset:0
	global_load_lds_dwordx4 v69, s[0:1] offset:1024
	global_load_lds_dwordx4 v70, s[0:1] offset:2048
	global_load_lds_dwordx4 v71, s[0:1] offset:3072
	s_add_u32 m0, s7, 0x8000
	s_nop 0
	global_load_lds_dwordx4 v68, s[2:3] offset:0
	global_load_lds_dwordx4 v69, s[2:3] offset:1024
	s_add_u32 s0, s0, 0x80
	s_addc_u32 s1, s1, 0
	s_add_u32 s2, s2, 0x80
	s_addc_u32 s3, s3, 0
	v_mov_b32_e32 v0, 0
	v_mov_b32_e32 v1, 0
	v_mov_b32_e32 v2, 0
	v_mov_b32_e32 v3, 0
	v_mov_b32_e32 v4, 0
	v_mov_b32_e32 v5, 0
	v_mov_b32_e32 v6, 0
	v_mov_b32_e32 v7, 0
	v_mov_b32_e32 v8, 0
	v_mov_b32_e32 v9, 0
	v_mov_b32_e32 v10, 0
	v_mov_b32_e32 v11, 0
	v_mov_b32_e32 v12, 0
	v_mov_b32_e32 v13, 0
	v_mov_b32_e32 v14, 0
	v_mov_b32_e32 v15, 0
	v_mov_b32_e32 v16, 0
	v_mov_b32_e32 v17, 0
	v_mov_b32_e32 v18, 0
	v_mov_b32_e32 v19, 0
	v_mov_b32_e32 v20, 0
	v_mov_b32_e32 v21, 0
	v_mov_b32_e32 v22, 0
	v_mov_b32_e32 v23, 0
	v_mov_b32_e32 v24, 0
	v_mov_b32_e32 v25, 0
	v_mov_b32_e32 v26, 0
	v_mov_b32_e32 v27, 0
	v_mov_b32_e32 v28, 0
	v_mov_b32_e32 v29, 0
	v_mov_b32_e32 v30, 0
	v_mov_b32_e32 v31, 0
	s_movk_i32 s8, 7
	s_waitcnt vmcnt(6)

.Leo_epi:
	s_waitcnt vmcnt(0)
	v_fmac_f32_e32 v96, v85, v0
	v_fmac_f32_e32 v97, v85, v1
	v_fmac_f32_e32 v98, v85, v2
	v_fmac_f32_e32 v99, v85, v3
	v_fmac_f32_e32 v100, v85, v4
	v_fmac_f32_e32 v101, v85, v5
	v_fmac_f32_e32 v102, v85, v6
	v_fmac_f32_e32 v103, v85, v7
	v_fmac_f32_e32 v104, v85, v8
	v_fmac_f32_e32 v105, v85, v9
	v_fmac_f32_e32 v106, v85, v10
	v_fmac_f32_e32 v107, v85, v11
	v_fmac_f32_e32 v108, v85, v12
	v_fmac_f32_e32 v109, v85, v13
	v_fmac_f32_e32 v110, v85, v14
	v_fmac_f32_e32 v111, v85, v15
	v_fmac_f32_e32 v112, v85, v16
	v_fmac_f32_e32 v113, v85, v17
	v_fmac_f32_e32 v114, v85, v18
	v_fmac_f32_e32 v115, v85, v19
	v_fmac_f32_e32 v116, v85, v20
	v_fmac_f32_e32 v117, v85, v21
	v_fmac_f32_e32 v118, v85, v22
	v_fmac_f32_e32 v119, v85, v23
	v_fmac_f32_e32 v120, v85, v24
	v_fmac_f32_e32 v121, v85, v25
	v_fmac_f32_e32 v122, v85, v26
	v_fmac_f32_e32 v123, v85, v27
	v_fmac_f32_e32 v124, v85, v28
	v_fmac_f32_e32 v125, v85, v29
	v_fmac_f32_e32 v126, v85, v30
	v_fmac_f32_e32 v127, v85, v31
	s_mov_b32 s16, s98
	s_mov_b32 s17, s99
	global_store_dword v83, v96, s[16:17] offset:0
	s_add_u32 s16, s16, 0x1000
	s_addc_u32 s17, s17, 0
	global_store_dword v83, v97, s[16:17] offset:0
	s_add_u32 s16, s16, 0x1000
	s_addc_u32 s17, s17, 0
	global_store_dword v83, v98, s[16:17] offset:0
	s_add_u32 s16, s16, 0x1000
	s_addc_u32 s17, s17, 0
	global_store_dword v83, v99, s[16:17] offset:0
	s_add_u32 s16, s16, 0x5000
	s_addc_u32 s17, s17, 0
	global_store_dword v83, v100, s[16:17] offset:0
	s_add_u32 s16, s16, 0x1000
	s_addc_u32 s17, s17, 0
	global_store_dword v83, v101, s[16:17] offset:0
	s_add_u32 s16, s16, 0x1000
	s_addc_u32 s17, s17, 0
	global_store_dword v83, v102, s[16:17] offset:0
	s_add_u32 s16, s16, 0x1000
	s_addc_u32 s17, s17, 0
	global_store_dword v83, v103, s[16:17] offset:0
	s_add_u32 s16, s16, 0x5000
	s_addc_u32 s17, s17, 0
	global_store_dword v83, v104, s[16:17] offset:0
	s_add_u32 s16, s16, 0x1000
	s_addc_u32 s17, s17, 0
	global_store_dword v83, v105, s[16:17] offset:0
	s_add_u32 s16, s16, 0x1000
	s_addc_u32 s17, s17, 0
	global_store_dword v83, v106, s[16:17] offset:0
	s_add_u32 s16, s16, 0x1000
	s_addc_u32 s17, s17, 0
	global_store_dword v83, v107, s[16:17] offset:0
	s_add_u32 s16, s16, 0x5000
	s_addc_u32 s17, s17, 0
	global_store_dword v83, v108, s[16:17] offset:0
	s_add_u32 s16, s16, 0x1000
	s_addc_u32 s17, s17, 0
	global_store_dword v83, v109, s[16:17] offset:0
	s_add_u32 s16, s16, 0x1000
	s_addc_u32 s17, s17, 0
	global_store_dword v83, v110, s[16:17] offset:0
	s_add_u32 s16, s16, 0x1000
	s_addc_u32 s17, s17, 0
	global_store_dword v83, v111, s[16:17] offset:0
	s_add_u32 s16, s16, 0x5000
	s_addc_u32 s17, s17, 0
	global_store_dword v83, v112, s[16:17] offset:0
	s_add_u32 s16, s16, 0x1000
	s_addc_u32 s17, s17, 0
	global_store_dword v83, v113, s[16:17] offset:0
	s_add_u32 s16, s16, 0x1000
	s_addc_u32 s17, s17, 0
	global_store_dword v83, v114, s[16:17] offset:0
	s_add_u32 s16, s16, 0x1000
	s_addc_u32 s17, s17, 0
	global_store_dword v83, v115, s[16:17] offset:0
	s_add_u32 s16, s16, 0x5000
	s_addc_u32 s17, s17, 0
	global_store_dword v83, v116, s[16:17] offset:0
	s_add_u32 s16, s16, 0x1000
	s_addc_u32 s17, s17, 0
	global_store_dword v83, v117, s[16:17] offset:0
	s_add_u32 s16, s16, 0x1000
	s_addc_u32 s17, s17, 0
	global_store_dword v83, v118, s[16:17] offset:0
	s_add_u32 s16, s16, 0x1000
	s_addc_u32 s17, s17, 0
	global_store_dword v83, v119, s[16:17] offset:0
	s_add_u32 s16, s16, 0x5000
	s_addc_u32 s17, s17, 0
	global_store_dword v83, v120, s[16:17] offset:0
	s_add_u32 s16, s16, 0x1000
	s_addc_u32 s17, s17, 0
	global_store_dword v83, v121, s[16:17] offset:0
	s_add_u32 s16, s16, 0x1000
	s_addc_u32 s17, s17, 0
	global_store_dword v83, v122, s[16:17] offset:0
	s_add_u32 s16, s16, 0x1000
	s_addc_u32 s17, s17, 0
	global_store_dword v83, v123, s[16:17] offset:0
	s_add_u32 s16, s16, 0x5000
	s_addc_u32 s17, s17, 0
	global_store_dword v83, v124, s[16:17] offset:0
	s_add_u32 s16, s16, 0x1000
	s_addc_u32 s17, s17, 0
	global_store_dword v83, v125, s[16:17] offset:0
	s_add_u32 s16, s16, 0x1000
	s_addc_u32 s17, s17, 0
	global_store_dword v83, v126, s[16:17] offset:0
	s_add_u32 s16, s16, 0x1000
	s_addc_u32 s17, s17, 0
	global_store_dword v83, v127, s[16:17] offset:0
	s_branch .Leo_next
